# phase0 rewritten by hand: 16B transposes + pipelined x->bf16
# speedup vs baseline: 1.0247x; 1.0247x over previous
.LBB0_5:
	s_or_b64 exec, exec, s[2:3]
	s_load_dwordx16 s[56:71], s[0:1], 0x0
	s_add_u32 s82, s86, 0x16ab000
	s_addc_u32 s83, s87, 0
	s_cmp_lt_i32 s88, 1
	s_cselect_b64 s[10:11], -1, 0
	s_waitcnt lgkmcnt(0)
	v_writelane_b32 v251, s56, 24
	s_cmp_gt_i32 s89, 0
	s_cselect_b64 s[0:1], -1, 0
	v_writelane_b32 v251, s57, 25
	v_writelane_b32 v251, s58, 26
	v_writelane_b32 v251, s59, 27
	v_writelane_b32 v251, s60, 28
	v_writelane_b32 v251, s61, 29
	v_writelane_b32 v251, s62, 30
	v_writelane_b32 v251, s63, 31
	v_writelane_b32 v251, s64, 32
	v_writelane_b32 v251, s65, 33
	v_writelane_b32 v251, s66, 34
	v_writelane_b32 v251, s67, 35
	v_writelane_b32 v251, s68, 36
	s_and_b64 s[0:1], s[10:11], s[0:1]
	v_writelane_b32 v251, s69, 37
	s_andn2_b64 vcc, exec, s[0:1]
	v_writelane_b32 v251, s70, 38
	v_writelane_b32 v251, s71, 39
	s_cbranch_vccnz .LBB0_144
	s_cmp_gt_i32 s88, -1
	s_cbranch_scc0 .LBB0_9
	s_branch .Lp0_start

.Lp0_start:
	v_and_b32_e32 v2, 15, v162
	v_lshrrev_b32_e32 v3, 4, v162
	s_mov_b32 s8, 0
	s_mov_b32 s9, 0
	s_mov_b32 s15, 0
	s_cmp_lt_u32 s92, 32
	s_cbranch_scc0 .Lp0_not_win
	v_readlane_b32 s12, v251, 34
	v_readlane_b32 s13, v251, 35
	s_lshl_b32 s0, s92, 8
	s_add_u32 s12, s12, s0
	s_addc_u32 s13, s13, 0
	s_movk_i32 s14, 0x2000
	s_lshl_b32 s0, s92, 17
	s_add_u32 s34, s86, s0
	s_addc_u32 s35, s87, 0
	s_movk_i32 s36, 0x800
	s_mov_b32 s8, 4
	s_branch .Lp0_decoded
.Lp0_not_win:
	s_cmp_lt_u32 s92, 48
	s_cbranch_scc0 .Lp0_not_wout
	v_readlane_b32 s12, v251, 5
	v_readlane_b32 s13, v251, 6
	s_sub_u32 s1, s92, 32
	s_lshl_b32 s0, s1, 8
	s_add_u32 s12, s12, s0
	s_addc_u32 s13, s13, 0
	s_movk_i32 s14, 0x1000
	s_lshl_b32 s0, s1, 17
	s_add_u32 s0, s0, 0x400000
	s_add_u32 s34, s86, s0
	s_addc_u32 s35, s87, 0
	s_movk_i32 s36, 0x800
	s_mov_b32 s8, 4
	s_branch .Lp0_decoded
.Lp0_not_wout:
	s_cmpk_lt_u32 s92, 0x88
	s_cbranch_scc0 .Lp0_not_gu
	s_sub_u32 s1, s92, 48
	s_cmp_ge_u32 s1, 44
	s_cbranch_scc1 .Lp0_up
	v_readlane_b32 s12, v251, 11
	v_readlane_b32 s13, v251, 12
	s_mov_b32 s2, 0
	s_branch .Lp0_gu_common
.Lp0_up:
	v_readlane_b32 s12, v251, 13
	v_readlane_b32 s13, v251, 14
	s_sub_u32 s1, s1, 44
	s_movk_i32 s2, 0x80
.Lp0_gu_common:
	s_lshl_b32 s0, s1, 8
	s_add_u32 s12, s12, s0
	s_addc_u32 s13, s13, 0
	s_movk_i32 s14, 0x2c00
	s_lshr_b32 s3, s1, 1
	s_lshl_b32 s3, s3, 8
	s_and_b32 s0, s1, 1
	s_lshl_b32 s0, s0, 6
	s_add_u32 s3, s3, s0
	s_add_u32 s3, s3, s2
	s_lshl_b32 s0, s3, 11
	s_add_u32 s0, s0, 0x600000
	s_add_u32 s34, s86, s0
	s_addc_u32 s35, s87, 0
	s_lshl_b32 s0, s3, 2
	s_add_u32 s1, s0, 0x16a0000
	s_add_u32 s42, s86, s1
	s_addc_u32 s43, s87, 0
	s_add_u32 s1, s0, 0x16a5800
	s_add_u32 s44, s86, s1
	s_addc_u32 s45, s87, 0
	v_readlane_b32 s38, v251, 7
	v_readlane_b32 s39, v251, 8
	v_readlane_b32 s40, v251, 9
	v_readlane_b32 s41, v251, 10
	s_movk_i32 s36, 0x800
	s_mov_b32 s8, 4
	s_mov_b32 s9, 1
	s_branch .Lp0_decoded
.Lp0_not_gu:
	s_cmpk_lt_u32 s92, 0xc8
	s_cbranch_scc0 .Lp0_not_wd
	v_readlane_b32 s12, v251, 15
	v_readlane_b32 s13, v251, 16
	s_sub_u32 s1, s92, 0x88
	s_and_b32 s2, s1, 15
	s_lshr_b32 s3, s1, 4
	s_mul_i32 s0, s3, 3
	s_lshl_b32 s1, s0, 20
	s_lshl_b32 s4, s2, 8
	s_add_u32 s1, s1, s4
	s_add_u32 s12, s12, s1
	s_addc_u32 s13, s13, 0
	s_movk_i32 s14, 0x1000
	s_mul_i32 s1, s2, 0x58000
	s_lshl_b32 s4, s0, 9
	s_add_u32 s1, s1, s4
	s_add_u32 s1, s1, 0x1100000
	s_add_u32 s34, s86, s1
	s_addc_u32 s35, s87, 0
	s_movk_i32 s36, 0x1600
	s_cmp_eq_u32 s3, 3
	s_cselect_b32 s8, 2, 3
	s_branch .Lp0_decoded
.Lp0_not_wd:
	s_cmpk_lt_u32 s92, 0xd0
	s_cbranch_scc0 .Lp0_xconv
	v_readlane_b32 s12, v251, 36
	v_readlane_b32 s13, v251, 37
	s_sub_u32 s1, s92, 0xc8
	s_lshr_b32 s2, s1, 1
	s_and_b32 s3, s1, 1
	s_lshl_b32 s0, s2, 16
	s_lshl_b32 s4, s3, 8
	s_add_u32 s0, s0, s4
	s_add_u32 s12, s12, s0
	s_addc_u32 s13, s13, 0
	s_movk_i32 s14, 0x200
	s_lshl_b32 s0, s2, 15
	s_lshl_b32 s4, s3, 14
	s_add_u32 s0, s0, s4
	s_add_u32 s0, s0, 0x1680000
	s_add_u32 s34, s86, s0
	s_addc_u32 s35, s87, 0
	s_movk_i32 s36, 0x100
	s_mov_b32 s8, 1
	s_mov_b32 s9, 2
.Lp0_decoded:
	s_lshl_b32 s0, s14, 3
	v_mul_lo_u32 v4, v3, s0
	v_lshl_add_u32 v4, v2, 4, v4
	v_lshrrev_b32_e32 v152, 3, v162
	v_and_b32_e32 v153, 7, v162
	v_and_b32_e32 v154, 15, v152
	v_lshrrev_b32_e32 v155, 4, v152
	v_lshl_or_b32 v156, v154, 2, v155
	v_mul_lo_u32 v5, v156, s36
	v_lshl_add_u32 v5, v153, 4, v5
	v_xor_b32_e32 v6, v3, v2
	v_lshlrev_b32_e32 v6, 4, v6
	v_lshl_add_u32 v6, v2, 11, v6
	v_lshlrev_b32_e32 v157, 9, v156
	v_mov_b32_e32 v158, v153
	v_xor_b32_e32 v158, v158, v154
	v_lshl_add_u32 v7, v158, 4, v157
	v_or_b32_e32 v158, 8, v153
	v_xor_b32_e32 v158, v158, v154
	v_lshl_add_u32 v8, v158, 4, v157
	v_or_b32_e32 v158, 16, v153
	v_xor_b32_e32 v158, v158, v154
	v_lshl_add_u32 v9, v158, 4, v157
	v_or_b32_e32 v158, 24, v153
	v_xor_b32_e32 v158, v158, v154
	v_lshl_add_u32 v10, v158, 4, v157
	v_lshlrev_b32_e32 v11, 5, v3
	v_mov_b32_e32 v144, 0
	v_mov_b32_e32 v145, 0
	v_mov_b32_e32 v146, 0
	v_mov_b32_e32 v147, 0
	v_mov_b32_e32 v148, 0
	v_mov_b32_e32 v149, 0
	v_mov_b32_e32 v150, 0
	v_mov_b32_e32 v151, 0
	v_readfirstlane_b32 s51, v162
	s_lshr_b32 s51, s51, 8
	s_lshr_b32 s0, s9, 1
	s_and_b32 s51, s51, s0
	s_cmp_eq_u32 s8, 0
	s_cbranch_scc1 .Lp0_xconv
	s_cmp_eq_u32 s51, 0
	s_cbranch_scc1 .Lp0_offok
	v_lshlrev_b32_e32 v4, 4, v2
.Lp0_offok:
	s_bitcmp1_b32 s9, 0
	s_cbranch_scc1 .Lp0_gate
	s_mov_b32 s16, s12
	s_mov_b32 s17, s13
	s_add_u32 s18, s16, s14
	s_addc_u32 s19, s17, 0
	s_add_u32 s20, s18, s14
	s_addc_u32 s21, s19, 0
	s_add_u32 s22, s20, s14
	s_addc_u32 s23, s21, 0
	s_add_u32 s24, s22, s14
	s_addc_u32 s25, s23, 0
	s_add_u32 s26, s24, s14
	s_addc_u32 s27, s25, 0
	s_add_u32 s28, s26, s14
	s_addc_u32 s29, s27, 0
	s_add_u32 s30, s28, s14
	s_addc_u32 s31, s29, 0
	global_load_dwordx4 v[16:19], v4, s[16:17]
	global_load_dwordx4 v[20:23], v4, s[18:19]
	global_load_dwordx4 v[24:27], v4, s[20:21]
	global_load_dwordx4 v[28:31], v4, s[22:23]
	global_load_dwordx4 v[32:35], v4, s[24:25]
	global_load_dwordx4 v[36:39], v4, s[26:27]
	global_load_dwordx4 v[40:43], v4, s[28:29]
	global_load_dwordx4 v[44:47], v4, s[30:31]
	s_sub_u32 s0, s8, 1
	s_min_u32 s0, s0, 1
	s_lshl_b32 s1, s14, 8
	s_mul_i32 s0, s0, s1
	s_add_u32 s16, s12, s0
	s_addc_u32 s17, s13, 0
	s_add_u32 s18, s16, s14
	s_addc_u32 s19, s17, 0
	s_add_u32 s20, s18, s14
	s_addc_u32 s21, s19, 0
	s_add_u32 s22, s20, s14
	s_addc_u32 s23, s21, 0
	s_add_u32 s24, s22, s14
	s_addc_u32 s25, s23, 0
	s_add_u32 s26, s24, s14
	s_addc_u32 s27, s25, 0
	s_add_u32 s28, s26, s14
	s_addc_u32 s29, s27, 0
	s_add_u32 s30, s28, s14
	s_addc_u32 s31, s29, 0
	global_load_dwordx4 v[48:51], v4, s[16:17]
	global_load_dwordx4 v[52:55], v4, s[18:19]
	global_load_dwordx4 v[56:59], v4, s[20:21]
	global_load_dwordx4 v[60:63], v4, s[22:23]
	global_load_dwordx4 v[64:67], v4, s[24:25]
	global_load_dwordx4 v[68:71], v4, s[26:27]
	global_load_dwordx4 v[72:75], v4, s[28:29]
	global_load_dwordx4 v[76:79], v4, s[30:31]
	s_waitcnt vmcnt(8)
	v_cvt_pk_bf16_f32 v80, v16, v20
	v_cvt_pk_bf16_f32 v81, v24, v28
	v_cvt_pk_bf16_f32 v82, v32, v36
	v_cvt_pk_bf16_f32 v83, v40, v44
	v_cvt_pk_bf16_f32 v84, v17, v21
	v_cvt_pk_bf16_f32 v85, v25, v29
	v_cvt_pk_bf16_f32 v86, v33, v37
	v_cvt_pk_bf16_f32 v87, v41, v45
	v_cvt_pk_bf16_f32 v88, v18, v22
	v_cvt_pk_bf16_f32 v89, v26, v30
	v_cvt_pk_bf16_f32 v90, v34, v38
	v_cvt_pk_bf16_f32 v91, v42, v46
	v_cvt_pk_bf16_f32 v92, v19, v23
	v_cvt_pk_bf16_f32 v93, v27, v31
	v_cvt_pk_bf16_f32 v94, v35, v39
	v_cvt_pk_bf16_f32 v95, v43, v47
	s_sub_u32 s0, s8, 1
	s_min_u32 s0, s0, 2
	s_lshl_b32 s1, s14, 8
	s_mul_i32 s0, s0, s1
	s_add_u32 s16, s12, s0
	s_addc_u32 s17, s13, 0
	s_add_u32 s18, s16, s14
	s_addc_u32 s19, s17, 0
	s_add_u32 s20, s18, s14
	s_addc_u32 s21, s19, 0
	s_add_u32 s22, s20, s14
	s_addc_u32 s23, s21, 0
	s_add_u32 s24, s22, s14
	s_addc_u32 s25, s23, 0
	s_add_u32 s26, s24, s14
	s_addc_u32 s27, s25, 0
	s_add_u32 s28, s26, s14
	s_addc_u32 s29, s27, 0
	s_add_u32 s30, s28, s14
	s_addc_u32 s31, s29, 0
	global_load_dwordx4 v[16:19], v4, s[16:17]
	global_load_dwordx4 v[20:23], v4, s[18:19]
	global_load_dwordx4 v[24:27], v4, s[20:21]
	global_load_dwordx4 v[28:31], v4, s[22:23]
	global_load_dwordx4 v[32:35], v4, s[24:25]
	global_load_dwordx4 v[36:39], v4, s[26:27]
	global_load_dwordx4 v[40:43], v4, s[28:29]
	global_load_dwordx4 v[44:47], v4, s[30:31]
	ds_write_b128 v6, v[80:83] offset:0
	ds_write_b128 v6, v[84:87] offset:512
	ds_write_b128 v6, v[88:91] offset:1024
	ds_write_b128 v6, v[92:95] offset:1536
	s_waitcnt lgkmcnt(0)
	s_barrier
	ds_read_b128 v[96:99], v7
	ds_read_b128 v[100:103], v8
	ds_read_b128 v[104:107], v9
	ds_read_b128 v[108:111], v10
	s_cmp_gt_u32 s8, 0
	s_cbranch_scc0 .Lp0_n_skipst0
	s_waitcnt lgkmcnt(3)
	global_store_dwordx4 v5, v[96:99], s[34:35]
	s_waitcnt lgkmcnt(2)
	global_store_dwordx4 v5, v[100:103], s[34:35] offset:128
	s_bitcmp1_b32 s9, 1
	s_cbranch_scc1 .Lp0_n_skipst0
	s_waitcnt lgkmcnt(1)
	global_store_dwordx4 v5, v[104:107], s[34:35] offset:256
	s_waitcnt lgkmcnt(0)
	global_store_dwordx4 v5, v[108:111], s[34:35] offset:384
.Lp0_n_skipst0:
	s_waitcnt lgkmcnt(0)
	s_waitcnt vmcnt(8)
	v_cvt_pk_bf16_f32 v80, v48, v52
	v_cvt_pk_bf16_f32 v81, v56, v60
	v_cvt_pk_bf16_f32 v82, v64, v68
	v_cvt_pk_bf16_f32 v83, v72, v76
	v_cvt_pk_bf16_f32 v84, v49, v53
	v_cvt_pk_bf16_f32 v85, v57, v61
	v_cvt_pk_bf16_f32 v86, v65, v69
	v_cvt_pk_bf16_f32 v87, v73, v77
	v_cvt_pk_bf16_f32 v88, v50, v54
	v_cvt_pk_bf16_f32 v89, v58, v62
	v_cvt_pk_bf16_f32 v90, v66, v70
	v_cvt_pk_bf16_f32 v91, v74, v78
	v_cvt_pk_bf16_f32 v92, v51, v55
	v_cvt_pk_bf16_f32 v93, v59, v63
	v_cvt_pk_bf16_f32 v94, v67, v71
	v_cvt_pk_bf16_f32 v95, v75, v79
	s_sub_u32 s0, s8, 1
	s_min_u32 s0, s0, 3
	s_lshl_b32 s1, s14, 8
	s_mul_i32 s0, s0, s1
	s_add_u32 s16, s12, s0
	s_addc_u32 s17, s13, 0
	s_add_u32 s18, s16, s14
	s_addc_u32 s19, s17, 0
	s_add_u32 s20, s18, s14
	s_addc_u32 s21, s19, 0
	s_add_u32 s22, s20, s14
	s_addc_u32 s23, s21, 0
	s_add_u32 s24, s22, s14
	s_addc_u32 s25, s23, 0
	s_add_u32 s26, s24, s14
	s_addc_u32 s27, s25, 0
	s_add_u32 s28, s26, s14
	s_addc_u32 s29, s27, 0
	s_add_u32 s30, s28, s14
	s_addc_u32 s31, s29, 0
	global_load_dwordx4 v[48:51], v4, s[16:17]
	global_load_dwordx4 v[52:55], v4, s[18:19]
	global_load_dwordx4 v[56:59], v4, s[20:21]
	global_load_dwordx4 v[60:63], v4, s[22:23]
	global_load_dwordx4 v[64:67], v4, s[24:25]
	global_load_dwordx4 v[68:71], v4, s[26:27]
	global_load_dwordx4 v[72:75], v4, s[28:29]
	global_load_dwordx4 v[76:79], v4, s[30:31]
	ds_write_b128 v6, v[80:83] offset:32768
	ds_write_b128 v6, v[84:87] offset:33280
	ds_write_b128 v6, v[88:91] offset:33792
	ds_write_b128 v6, v[92:95] offset:34304
	s_waitcnt lgkmcnt(0)
	s_barrier
	ds_read_b128 v[96:99], v7 offset:32768
	ds_read_b128 v[100:103], v8 offset:32768
	ds_read_b128 v[104:107], v9 offset:32768
	ds_read_b128 v[108:111], v10 offset:32768
	s_cmp_gt_u32 s8, 1
	s_cbranch_scc0 .Lp0_n_skipst1
	s_waitcnt lgkmcnt(3)
	global_store_dwordx4 v5, v[96:99], s[34:35] offset:512
	s_waitcnt lgkmcnt(2)
	global_store_dwordx4 v5, v[100:103], s[34:35] offset:640
	s_bitcmp1_b32 s9, 1
	s_cbranch_scc1 .Lp0_n_skipst1
	s_waitcnt lgkmcnt(1)
	global_store_dwordx4 v5, v[104:107], s[34:35] offset:768
	s_waitcnt lgkmcnt(0)
	global_store_dwordx4 v5, v[108:111], s[34:35] offset:896
.Lp0_n_skipst1:
	s_waitcnt lgkmcnt(0)
	s_waitcnt vmcnt(8)
	v_cvt_pk_bf16_f32 v80, v16, v20
	v_cvt_pk_bf16_f32 v81, v24, v28
	v_cvt_pk_bf16_f32 v82, v32, v36
	v_cvt_pk_bf16_f32 v83, v40, v44
	v_cvt_pk_bf16_f32 v84, v17, v21
	v_cvt_pk_bf16_f32 v85, v25, v29
	v_cvt_pk_bf16_f32 v86, v33, v37
	v_cvt_pk_bf16_f32 v87, v41, v45
	v_cvt_pk_bf16_f32 v88, v18, v22
	v_cvt_pk_bf16_f32 v89, v26, v30
	v_cvt_pk_bf16_f32 v90, v34, v38
	v_cvt_pk_bf16_f32 v91, v42, v46
	v_cvt_pk_bf16_f32 v92, v19, v23
	v_cvt_pk_bf16_f32 v93, v27, v31
	v_cvt_pk_bf16_f32 v94, v35, v39
	v_cvt_pk_bf16_f32 v95, v43, v47
	ds_write_b128 v6, v[80:83] offset:0
	ds_write_b128 v6, v[84:87] offset:512
	ds_write_b128 v6, v[88:91] offset:1024
	ds_write_b128 v6, v[92:95] offset:1536
	s_waitcnt lgkmcnt(0)
	s_barrier
	ds_read_b128 v[96:99], v7
	ds_read_b128 v[100:103], v8
	ds_read_b128 v[104:107], v9
	ds_read_b128 v[108:111], v10
	s_cmp_gt_u32 s8, 2
	s_cbranch_scc0 .Lp0_n_skipst2
	s_waitcnt lgkmcnt(3)
	global_store_dwordx4 v5, v[96:99], s[34:35] offset:1024
	s_waitcnt lgkmcnt(2)
	global_store_dwordx4 v5, v[100:103], s[34:35] offset:1152
	s_bitcmp1_b32 s9, 1
	s_cbranch_scc1 .Lp0_n_skipst2
	s_waitcnt lgkmcnt(1)
	global_store_dwordx4 v5, v[104:107], s[34:35] offset:1280
	s_waitcnt lgkmcnt(0)
	global_store_dwordx4 v5, v[108:111], s[34:35] offset:1408
.Lp0_n_skipst2:
	s_waitcnt lgkmcnt(0)
	s_waitcnt vmcnt(0)
	v_cvt_pk_bf16_f32 v80, v48, v52
	v_cvt_pk_bf16_f32 v81, v56, v60
	v_cvt_pk_bf16_f32 v82, v64, v68
	v_cvt_pk_bf16_f32 v83, v72, v76
	v_cvt_pk_bf16_f32 v84, v49, v53
	v_cvt_pk_bf16_f32 v85, v57, v61
	v_cvt_pk_bf16_f32 v86, v65, v69
	v_cvt_pk_bf16_f32 v87, v73, v77
	v_cvt_pk_bf16_f32 v88, v50, v54
	v_cvt_pk_bf16_f32 v89, v58, v62
	v_cvt_pk_bf16_f32 v90, v66, v70
	v_cvt_pk_bf16_f32 v91, v74, v78
	v_cvt_pk_bf16_f32 v92, v51, v55
	v_cvt_pk_bf16_f32 v93, v59, v63
	v_cvt_pk_bf16_f32 v94, v67, v71
	v_cvt_pk_bf16_f32 v95, v75, v79
	ds_write_b128 v6, v[80:83] offset:32768
	ds_write_b128 v6, v[84:87] offset:33280
	ds_write_b128 v6, v[88:91] offset:33792
	ds_write_b128 v6, v[92:95] offset:34304
	s_waitcnt lgkmcnt(0)
	s_barrier
	ds_read_b128 v[96:99], v7 offset:32768
	ds_read_b128 v[100:103], v8 offset:32768
	ds_read_b128 v[104:107], v9 offset:32768
	ds_read_b128 v[108:111], v10 offset:32768
	s_cmp_gt_u32 s8, 3
	s_cbranch_scc0 .Lp0_n_skipst3
	s_waitcnt lgkmcnt(3)
	global_store_dwordx4 v5, v[96:99], s[34:35] offset:1536
	s_waitcnt lgkmcnt(2)
	global_store_dwordx4 v5, v[100:103], s[34:35] offset:1664
	s_bitcmp1_b32 s9, 1
	s_cbranch_scc1 .Lp0_n_skipst3
	s_waitcnt lgkmcnt(1)
	global_store_dwordx4 v5, v[104:107], s[34:35] offset:1792
	s_waitcnt lgkmcnt(0)
	global_store_dwordx4 v5, v[108:111], s[34:35] offset:1920
.Lp0_n_skipst3:
	s_waitcnt lgkmcnt(0)
	s_branch .Lp0_xconv
.Lp0_gate:
	s_mov_b32 s16, s12
	s_mov_b32 s17, s13
	s_add_u32 s18, s16, s14
	s_addc_u32 s19, s17, 0
	s_add_u32 s20, s18, s14
	s_addc_u32 s21, s19, 0
	s_add_u32 s22, s20, s14
	s_addc_u32 s23, s21, 0
	s_add_u32 s24, s22, s14
	s_addc_u32 s25, s23, 0
	s_add_u32 s26, s24, s14
	s_addc_u32 s27, s25, 0
	s_add_u32 s28, s26, s14
	s_addc_u32 s29, s27, 0
	s_add_u32 s30, s28, s14
	s_addc_u32 s31, s29, 0
	global_load_dwordx4 v[16:19], v4, s[16:17]
	global_load_dwordx4 v[20:23], v4, s[18:19]
	global_load_dwordx4 v[24:27], v4, s[20:21]
	global_load_dwordx4 v[28:31], v4, s[22:23]
	global_load_dwordx4 v[32:35], v4, s[24:25]
	global_load_dwordx4 v[36:39], v4, s[26:27]
	global_load_dwordx4 v[40:43], v4, s[28:29]
	global_load_dwordx4 v[44:47], v4, s[30:31]
	global_load_dwordx4 v[112:115], v11, s[38:39] offset:0
	global_load_dwordx4 v[116:119], v11, s[38:39] offset:16
	global_load_dwordx4 v[120:123], v11, s[40:41] offset:0
	global_load_dwordx4 v[124:127], v11, s[40:41] offset:16
	s_sub_u32 s0, s8, 1
	s_min_u32 s0, s0, 1
	s_lshl_b32 s1, s14, 8
	s_mul_i32 s0, s0, s1
	s_add_u32 s16, s12, s0
	s_addc_u32 s17, s13, 0
	s_add_u32 s18, s16, s14
	s_addc_u32 s19, s17, 0
	s_add_u32 s20, s18, s14
	s_addc_u32 s21, s19, 0
	s_add_u32 s22, s20, s14
	s_addc_u32 s23, s21, 0
	s_add_u32 s24, s22, s14
	s_addc_u32 s25, s23, 0
	s_add_u32 s26, s24, s14
	s_addc_u32 s27, s25, 0
	s_add_u32 s28, s26, s14
	s_addc_u32 s29, s27, 0
	s_add_u32 s30, s28, s14
	s_addc_u32 s31, s29, 0
	global_load_dwordx4 v[48:51], v4, s[16:17]
	global_load_dwordx4 v[52:55], v4, s[18:19]
	global_load_dwordx4 v[56:59], v4, s[20:21]
	global_load_dwordx4 v[60:63], v4, s[22:23]
	global_load_dwordx4 v[64:67], v4, s[24:25]
	global_load_dwordx4 v[68:71], v4, s[26:27]
	global_load_dwordx4 v[72:75], v4, s[28:29]
	global_load_dwordx4 v[76:79], v4, s[30:31]
	global_load_dwordx4 v[128:131], v11, s[38:39] offset:1024
	global_load_dwordx4 v[132:135], v11, s[38:39] offset:1040
	global_load_dwordx4 v[136:139], v11, s[40:41] offset:1024
	global_load_dwordx4 v[140:143], v11, s[40:41] offset:1040
	s_waitcnt vmcnt(12)
	v_fmac_f32_e32 v148, v120, v16
	v_fmac_f32_e32 v148, v121, v20
	v_fmac_f32_e32 v148, v122, v24
	v_fmac_f32_e32 v148, v123, v28
	v_fmac_f32_e32 v148, v124, v32
	v_fmac_f32_e32 v148, v125, v36
	v_fmac_f32_e32 v148, v126, v40
	v_fmac_f32_e32 v148, v127, v44
	v_fmac_f32_e32 v149, v120, v17
	v_fmac_f32_e32 v149, v121, v21
	v_fmac_f32_e32 v149, v122, v25
	v_fmac_f32_e32 v149, v123, v29
	v_fmac_f32_e32 v149, v124, v33
	v_fmac_f32_e32 v149, v125, v37
	v_fmac_f32_e32 v149, v126, v41
	v_fmac_f32_e32 v149, v127, v45
	v_fmac_f32_e32 v150, v120, v18
	v_fmac_f32_e32 v150, v121, v22
	v_fmac_f32_e32 v150, v122, v26
	v_fmac_f32_e32 v150, v123, v30
	v_fmac_f32_e32 v150, v124, v34
	v_fmac_f32_e32 v150, v125, v38
	v_fmac_f32_e32 v150, v126, v42
	v_fmac_f32_e32 v150, v127, v46
	v_fmac_f32_e32 v151, v120, v19
	v_fmac_f32_e32 v151, v121, v23
	v_fmac_f32_e32 v151, v122, v27
	v_fmac_f32_e32 v151, v123, v31
	v_fmac_f32_e32 v151, v124, v35
	v_fmac_f32_e32 v151, v125, v39
	v_fmac_f32_e32 v151, v126, v43
	v_fmac_f32_e32 v151, v127, v47
	v_mul_f32_e32 v16, v112, v16
	v_mul_f32_e32 v17, v112, v17
	v_mul_f32_e32 v18, v112, v18
	v_mul_f32_e32 v19, v112, v19
	v_mul_f32_e32 v20, v113, v20
	v_mul_f32_e32 v21, v113, v21
	v_mul_f32_e32 v22, v113, v22
	v_mul_f32_e32 v23, v113, v23
	v_mul_f32_e32 v24, v114, v24
	v_mul_f32_e32 v25, v114, v25
	v_mul_f32_e32 v26, v114, v26
	v_mul_f32_e32 v27, v114, v27
	v_mul_f32_e32 v28, v115, v28
	v_mul_f32_e32 v29, v115, v29
	v_mul_f32_e32 v30, v115, v30
	v_mul_f32_e32 v31, v115, v31
	v_mul_f32_e32 v32, v116, v32
	v_mul_f32_e32 v33, v116, v33
	v_mul_f32_e32 v34, v116, v34
	v_mul_f32_e32 v35, v116, v35
	v_mul_f32_e32 v36, v117, v36
	v_mul_f32_e32 v37, v117, v37
	v_mul_f32_e32 v38, v117, v38
	v_mul_f32_e32 v39, v117, v39
	v_mul_f32_e32 v40, v118, v40
	v_mul_f32_e32 v41, v118, v41
	v_mul_f32_e32 v42, v118, v42
	v_mul_f32_e32 v43, v118, v43
	v_mul_f32_e32 v44, v119, v44
	v_mul_f32_e32 v45, v119, v45
	v_mul_f32_e32 v46, v119, v46
	v_mul_f32_e32 v47, v119, v47
	v_cvt_pk_bf16_f32 v80, v16, v20
	v_cvt_pk_bf16_f32 v81, v24, v28
	v_cvt_pk_bf16_f32 v82, v32, v36
	v_cvt_pk_bf16_f32 v83, v40, v44
	v_cvt_pk_bf16_f32 v84, v17, v21
	v_cvt_pk_bf16_f32 v85, v25, v29
	v_cvt_pk_bf16_f32 v86, v33, v37
	v_cvt_pk_bf16_f32 v87, v41, v45
	v_cvt_pk_bf16_f32 v88, v18, v22
	v_cvt_pk_bf16_f32 v89, v26, v30
	v_cvt_pk_bf16_f32 v90, v34, v38
	v_cvt_pk_bf16_f32 v91, v42, v46
	v_cvt_pk_bf16_f32 v92, v19, v23
	v_cvt_pk_bf16_f32 v93, v27, v31
	v_cvt_pk_bf16_f32 v94, v35, v39
	v_cvt_pk_bf16_f32 v95, v43, v47
	v_lshlrev_b32_e32 v152, 16, v80
	v_and_b32_e32 v153, 0xffff0000, v80
	v_add_f32_e32 v144, v144, v152
	v_add_f32_e32 v144, v144, v153
	v_lshlrev_b32_e32 v152, 16, v81
	v_and_b32_e32 v153, 0xffff0000, v81
	v_add_f32_e32 v144, v144, v152
	v_add_f32_e32 v144, v144, v153
	v_lshlrev_b32_e32 v152, 16, v82
	v_and_b32_e32 v153, 0xffff0000, v82
	v_add_f32_e32 v144, v144, v152
	v_add_f32_e32 v144, v144, v153
	v_lshlrev_b32_e32 v152, 16, v83
	v_and_b32_e32 v153, 0xffff0000, v83
	v_add_f32_e32 v144, v144, v152
	v_add_f32_e32 v144, v144, v153
	v_lshlrev_b32_e32 v152, 16, v84
	v_and_b32_e32 v153, 0xffff0000, v84
	v_add_f32_e32 v145, v145, v152
	v_add_f32_e32 v145, v145, v153
	v_lshlrev_b32_e32 v152, 16, v85
	v_and_b32_e32 v153, 0xffff0000, v85
	v_add_f32_e32 v145, v145, v152
	v_add_f32_e32 v145, v145, v153
	v_lshlrev_b32_e32 v152, 16, v86
	v_and_b32_e32 v153, 0xffff0000, v86
	v_add_f32_e32 v145, v145, v152
	v_add_f32_e32 v145, v145, v153
	v_lshlrev_b32_e32 v152, 16, v87
	v_and_b32_e32 v153, 0xffff0000, v87
	v_add_f32_e32 v145, v145, v152
	v_add_f32_e32 v145, v145, v153
	v_lshlrev_b32_e32 v152, 16, v88
	v_and_b32_e32 v153, 0xffff0000, v88
	v_add_f32_e32 v146, v146, v152
	v_add_f32_e32 v146, v146, v153
	v_lshlrev_b32_e32 v152, 16, v89
	v_and_b32_e32 v153, 0xffff0000, v89
	v_add_f32_e32 v146, v146, v152
	v_add_f32_e32 v146, v146, v153
	v_lshlrev_b32_e32 v152, 16, v90
	v_and_b32_e32 v153, 0xffff0000, v90
	v_add_f32_e32 v146, v146, v152
	v_add_f32_e32 v146, v146, v153
	v_lshlrev_b32_e32 v152, 16, v91
	v_and_b32_e32 v153, 0xffff0000, v91
	v_add_f32_e32 v146, v146, v152
	v_add_f32_e32 v146, v146, v153
	v_lshlrev_b32_e32 v152, 16, v92
	v_and_b32_e32 v153, 0xffff0000, v92
	v_add_f32_e32 v147, v147, v152
	v_add_f32_e32 v147, v147, v153
	v_lshlrev_b32_e32 v152, 16, v93
	v_and_b32_e32 v153, 0xffff0000, v93
	v_add_f32_e32 v147, v147, v152
	v_add_f32_e32 v147, v147, v153
	v_lshlrev_b32_e32 v152, 16, v94
	v_and_b32_e32 v153, 0xffff0000, v94
	v_add_f32_e32 v147, v147, v152
	v_add_f32_e32 v147, v147, v153
	v_lshlrev_b32_e32 v152, 16, v95
	v_and_b32_e32 v153, 0xffff0000, v95
	v_add_f32_e32 v147, v147, v152
	v_add_f32_e32 v147, v147, v153
	s_sub_u32 s0, s8, 1
	s_min_u32 s0, s0, 2
	s_lshl_b32 s1, s14, 8
	s_mul_i32 s0, s0, s1
	s_add_u32 s16, s12, s0
	s_addc_u32 s17, s13, 0
	s_add_u32 s18, s16, s14
	s_addc_u32 s19, s17, 0
	s_add_u32 s20, s18, s14
	s_addc_u32 s21, s19, 0
	s_add_u32 s22, s20, s14
	s_addc_u32 s23, s21, 0
	s_add_u32 s24, s22, s14
	s_addc_u32 s25, s23, 0
	s_add_u32 s26, s24, s14
	s_addc_u32 s27, s25, 0
	s_add_u32 s28, s26, s14
	s_addc_u32 s29, s27, 0
	s_add_u32 s30, s28, s14
	s_addc_u32 s31, s29, 0
	global_load_dwordx4 v[16:19], v4, s[16:17]
	global_load_dwordx4 v[20:23], v4, s[18:19]
	global_load_dwordx4 v[24:27], v4, s[20:21]
	global_load_dwordx4 v[28:31], v4, s[22:23]
	global_load_dwordx4 v[32:35], v4, s[24:25]
	global_load_dwordx4 v[36:39], v4, s[26:27]
	global_load_dwordx4 v[40:43], v4, s[28:29]
	global_load_dwordx4 v[44:47], v4, s[30:31]
	global_load_dwordx4 v[112:115], v11, s[38:39] offset:2048
	global_load_dwordx4 v[116:119], v11, s[38:39] offset:2064
	global_load_dwordx4 v[120:123], v11, s[40:41] offset:2048
	global_load_dwordx4 v[124:127], v11, s[40:41] offset:2064
	ds_write_b128 v6, v[80:83] offset:0
	ds_write_b128 v6, v[84:87] offset:512
	ds_write_b128 v6, v[88:91] offset:1024
	ds_write_b128 v6, v[92:95] offset:1536
	s_waitcnt lgkmcnt(0)
	s_barrier
	ds_read_b128 v[96:99], v7
	ds_read_b128 v[100:103], v8
	ds_read_b128 v[104:107], v9
	ds_read_b128 v[108:111], v10
	s_cmp_gt_u32 s8, 0
	s_cbranch_scc0 .Lp0_g_skipst0
	s_waitcnt lgkmcnt(3)
	global_store_dwordx4 v5, v[96:99], s[34:35]
	s_waitcnt lgkmcnt(2)
	global_store_dwordx4 v5, v[100:103], s[34:35] offset:128
	s_bitcmp1_b32 s9, 1
	s_cbranch_scc1 .Lp0_g_skipst0
	s_waitcnt lgkmcnt(1)
	global_store_dwordx4 v5, v[104:107], s[34:35] offset:256
	s_waitcnt lgkmcnt(0)
	global_store_dwordx4 v5, v[108:111], s[34:35] offset:384
.Lp0_g_skipst0:
	s_waitcnt lgkmcnt(0)
	s_waitcnt vmcnt(12)
	v_fmac_f32_e32 v148, v136, v48
	v_fmac_f32_e32 v148, v137, v52
	v_fmac_f32_e32 v148, v138, v56
	v_fmac_f32_e32 v148, v139, v60
	v_fmac_f32_e32 v148, v140, v64
	v_fmac_f32_e32 v148, v141, v68
	v_fmac_f32_e32 v148, v142, v72
	v_fmac_f32_e32 v148, v143, v76
	v_fmac_f32_e32 v149, v136, v49
	v_fmac_f32_e32 v149, v137, v53
	v_fmac_f32_e32 v149, v138, v57
	v_fmac_f32_e32 v149, v139, v61
	v_fmac_f32_e32 v149, v140, v65
	v_fmac_f32_e32 v149, v141, v69
	v_fmac_f32_e32 v149, v142, v73
	v_fmac_f32_e32 v149, v143, v77
	v_fmac_f32_e32 v150, v136, v50
	v_fmac_f32_e32 v150, v137, v54
	v_fmac_f32_e32 v150, v138, v58
	v_fmac_f32_e32 v150, v139, v62
	v_fmac_f32_e32 v150, v140, v66
	v_fmac_f32_e32 v150, v141, v70
	v_fmac_f32_e32 v150, v142, v74
	v_fmac_f32_e32 v150, v143, v78
	v_fmac_f32_e32 v151, v136, v51
	v_fmac_f32_e32 v151, v137, v55
	v_fmac_f32_e32 v151, v138, v59
	v_fmac_f32_e32 v151, v139, v63
	v_fmac_f32_e32 v151, v140, v67
	v_fmac_f32_e32 v151, v141, v71
	v_fmac_f32_e32 v151, v142, v75
	v_fmac_f32_e32 v151, v143, v79
	v_mul_f32_e32 v48, v128, v48
	v_mul_f32_e32 v49, v128, v49
	v_mul_f32_e32 v50, v128, v50
	v_mul_f32_e32 v51, v128, v51
	v_mul_f32_e32 v52, v129, v52
	v_mul_f32_e32 v53, v129, v53
	v_mul_f32_e32 v54, v129, v54
	v_mul_f32_e32 v55, v129, v55
	v_mul_f32_e32 v56, v130, v56
	v_mul_f32_e32 v57, v130, v57
	v_mul_f32_e32 v58, v130, v58
	v_mul_f32_e32 v59, v130, v59
	v_mul_f32_e32 v60, v131, v60
	v_mul_f32_e32 v61, v131, v61
	v_mul_f32_e32 v62, v131, v62
	v_mul_f32_e32 v63, v131, v63
	v_mul_f32_e32 v64, v132, v64
	v_mul_f32_e32 v65, v132, v65
	v_mul_f32_e32 v66, v132, v66
	v_mul_f32_e32 v67, v132, v67
	v_mul_f32_e32 v68, v133, v68
	v_mul_f32_e32 v69, v133, v69
	v_mul_f32_e32 v70, v133, v70
	v_mul_f32_e32 v71, v133, v71
	v_mul_f32_e32 v72, v134, v72
	v_mul_f32_e32 v73, v134, v73
	v_mul_f32_e32 v74, v134, v74
	v_mul_f32_e32 v75, v134, v75
	v_mul_f32_e32 v76, v135, v76
	v_mul_f32_e32 v77, v135, v77
	v_mul_f32_e32 v78, v135, v78
	v_mul_f32_e32 v79, v135, v79
	v_cvt_pk_bf16_f32 v80, v48, v52
	v_cvt_pk_bf16_f32 v81, v56, v60
	v_cvt_pk_bf16_f32 v82, v64, v68
	v_cvt_pk_bf16_f32 v83, v72, v76
	v_cvt_pk_bf16_f32 v84, v49, v53
	v_cvt_pk_bf16_f32 v85, v57, v61
	v_cvt_pk_bf16_f32 v86, v65, v69
	v_cvt_pk_bf16_f32 v87, v73, v77
	v_cvt_pk_bf16_f32 v88, v50, v54
	v_cvt_pk_bf16_f32 v89, v58, v62
	v_cvt_pk_bf16_f32 v90, v66, v70
	v_cvt_pk_bf16_f32 v91, v74, v78
	v_cvt_pk_bf16_f32 v92, v51, v55
	v_cvt_pk_bf16_f32 v93, v59, v63
	v_cvt_pk_bf16_f32 v94, v67, v71
	v_cvt_pk_bf16_f32 v95, v75, v79
	v_lshlrev_b32_e32 v152, 16, v80
	v_and_b32_e32 v153, 0xffff0000, v80
	v_add_f32_e32 v144, v144, v152
	v_add_f32_e32 v144, v144, v153
	v_lshlrev_b32_e32 v152, 16, v81
	v_and_b32_e32 v153, 0xffff0000, v81
	v_add_f32_e32 v144, v144, v152
	v_add_f32_e32 v144, v144, v153
	v_lshlrev_b32_e32 v152, 16, v82
	v_and_b32_e32 v153, 0xffff0000, v82
	v_add_f32_e32 v144, v144, v152
	v_add_f32_e32 v144, v144, v153
	v_lshlrev_b32_e32 v152, 16, v83
	v_and_b32_e32 v153, 0xffff0000, v83
	v_add_f32_e32 v144, v144, v152
	v_add_f32_e32 v144, v144, v153
	v_lshlrev_b32_e32 v152, 16, v84
	v_and_b32_e32 v153, 0xffff0000, v84
	v_add_f32_e32 v145, v145, v152
	v_add_f32_e32 v145, v145, v153
	v_lshlrev_b32_e32 v152, 16, v85
	v_and_b32_e32 v153, 0xffff0000, v85
	v_add_f32_e32 v145, v145, v152
	v_add_f32_e32 v145, v145, v153
	v_lshlrev_b32_e32 v152, 16, v86
	v_and_b32_e32 v153, 0xffff0000, v86
	v_add_f32_e32 v145, v145, v152
	v_add_f32_e32 v145, v145, v153
	v_lshlrev_b32_e32 v152, 16, v87
	v_and_b32_e32 v153, 0xffff0000, v87
	v_add_f32_e32 v145, v145, v152
	v_add_f32_e32 v145, v145, v153
	v_lshlrev_b32_e32 v152, 16, v88
	v_and_b32_e32 v153, 0xffff0000, v88
	v_add_f32_e32 v146, v146, v152
	v_add_f32_e32 v146, v146, v153
	v_lshlrev_b32_e32 v152, 16, v89
	v_and_b32_e32 v153, 0xffff0000, v89
	v_add_f32_e32 v146, v146, v152
	v_add_f32_e32 v146, v146, v153
	v_lshlrev_b32_e32 v152, 16, v90
	v_and_b32_e32 v153, 0xffff0000, v90
	v_add_f32_e32 v146, v146, v152
	v_add_f32_e32 v146, v146, v153
	v_lshlrev_b32_e32 v152, 16, v91
	v_and_b32_e32 v153, 0xffff0000, v91
	v_add_f32_e32 v146, v146, v152
	v_add_f32_e32 v146, v146, v153
	v_lshlrev_b32_e32 v152, 16, v92
	v_and_b32_e32 v153, 0xffff0000, v92
	v_add_f32_e32 v147, v147, v152
	v_add_f32_e32 v147, v147, v153
	v_lshlrev_b32_e32 v152, 16, v93
	v_and_b32_e32 v153, 0xffff0000, v93
	v_add_f32_e32 v147, v147, v152
	v_add_f32_e32 v147, v147, v153
	v_lshlrev_b32_e32 v152, 16, v94
	v_and_b32_e32 v153, 0xffff0000, v94
	v_add_f32_e32 v147, v147, v152
	v_add_f32_e32 v147, v147, v153
	v_lshlrev_b32_e32 v152, 16, v95
	v_and_b32_e32 v153, 0xffff0000, v95
	v_add_f32_e32 v147, v147, v152
	v_add_f32_e32 v147, v147, v153
	s_sub_u32 s0, s8, 1
	s_min_u32 s0, s0, 3
	s_lshl_b32 s1, s14, 8
	s_mul_i32 s0, s0, s1
	s_add_u32 s16, s12, s0
	s_addc_u32 s17, s13, 0
	s_add_u32 s18, s16, s14
	s_addc_u32 s19, s17, 0
	s_add_u32 s20, s18, s14
	s_addc_u32 s21, s19, 0
	s_add_u32 s22, s20, s14
	s_addc_u32 s23, s21, 0
	s_add_u32 s24, s22, s14
	s_addc_u32 s25, s23, 0
	s_add_u32 s26, s24, s14
	s_addc_u32 s27, s25, 0
	s_add_u32 s28, s26, s14
	s_addc_u32 s29, s27, 0
	s_add_u32 s30, s28, s14
	s_addc_u32 s31, s29, 0
	global_load_dwordx4 v[48:51], v4, s[16:17]
	global_load_dwordx4 v[52:55], v4, s[18:19]
	global_load_dwordx4 v[56:59], v4, s[20:21]
	global_load_dwordx4 v[60:63], v4, s[22:23]
	global_load_dwordx4 v[64:67], v4, s[24:25]
	global_load_dwordx4 v[68:71], v4, s[26:27]
	global_load_dwordx4 v[72:75], v4, s[28:29]
	global_load_dwordx4 v[76:79], v4, s[30:31]
	global_load_dwordx4 v[128:131], v11, s[38:39] offset:3072
	global_load_dwordx4 v[132:135], v11, s[38:39] offset:3088
	global_load_dwordx4 v[136:139], v11, s[40:41] offset:3072
	global_load_dwordx4 v[140:143], v11, s[40:41] offset:3088
	ds_write_b128 v6, v[80:83] offset:32768
	ds_write_b128 v6, v[84:87] offset:33280
	ds_write_b128 v6, v[88:91] offset:33792
	ds_write_b128 v6, v[92:95] offset:34304
	s_waitcnt lgkmcnt(0)
	s_barrier
	ds_read_b128 v[96:99], v7 offset:32768
	ds_read_b128 v[100:103], v8 offset:32768
	ds_read_b128 v[104:107], v9 offset:32768
	ds_read_b128 v[108:111], v10 offset:32768
	s_cmp_gt_u32 s8, 1
	s_cbranch_scc0 .Lp0_g_skipst1
	s_waitcnt lgkmcnt(3)
	global_store_dwordx4 v5, v[96:99], s[34:35] offset:512
	s_waitcnt lgkmcnt(2)
	global_store_dwordx4 v5, v[100:103], s[34:35] offset:640
	s_bitcmp1_b32 s9, 1
	s_cbranch_scc1 .Lp0_g_skipst1
	s_waitcnt lgkmcnt(1)
	global_store_dwordx4 v5, v[104:107], s[34:35] offset:768
	s_waitcnt lgkmcnt(0)
	global_store_dwordx4 v5, v[108:111], s[34:35] offset:896
.Lp0_g_skipst1:
	s_waitcnt lgkmcnt(0)
	s_waitcnt vmcnt(12)
	v_fmac_f32_e32 v148, v120, v16
	v_fmac_f32_e32 v148, v121, v20
	v_fmac_f32_e32 v148, v122, v24
	v_fmac_f32_e32 v148, v123, v28
	v_fmac_f32_e32 v148, v124, v32
	v_fmac_f32_e32 v148, v125, v36
	v_fmac_f32_e32 v148, v126, v40
	v_fmac_f32_e32 v148, v127, v44
	v_fmac_f32_e32 v149, v120, v17
	v_fmac_f32_e32 v149, v121, v21
	v_fmac_f32_e32 v149, v122, v25
	v_fmac_f32_e32 v149, v123, v29
	v_fmac_f32_e32 v149, v124, v33
	v_fmac_f32_e32 v149, v125, v37
	v_fmac_f32_e32 v149, v126, v41
	v_fmac_f32_e32 v149, v127, v45
	v_fmac_f32_e32 v150, v120, v18
	v_fmac_f32_e32 v150, v121, v22
	v_fmac_f32_e32 v150, v122, v26
	v_fmac_f32_e32 v150, v123, v30
	v_fmac_f32_e32 v150, v124, v34
	v_fmac_f32_e32 v150, v125, v38
	v_fmac_f32_e32 v150, v126, v42
	v_fmac_f32_e32 v150, v127, v46
	v_fmac_f32_e32 v151, v120, v19
	v_fmac_f32_e32 v151, v121, v23
	v_fmac_f32_e32 v151, v122, v27
	v_fmac_f32_e32 v151, v123, v31
	v_fmac_f32_e32 v151, v124, v35
	v_fmac_f32_e32 v151, v125, v39
	v_fmac_f32_e32 v151, v126, v43
	v_fmac_f32_e32 v151, v127, v47
	v_mul_f32_e32 v16, v112, v16
	v_mul_f32_e32 v17, v112, v17
	v_mul_f32_e32 v18, v112, v18
	v_mul_f32_e32 v19, v112, v19
	v_mul_f32_e32 v20, v113, v20
	v_mul_f32_e32 v21, v113, v21
	v_mul_f32_e32 v22, v113, v22
	v_mul_f32_e32 v23, v113, v23
	v_mul_f32_e32 v24, v114, v24
	v_mul_f32_e32 v25, v114, v25
	v_mul_f32_e32 v26, v114, v26
	v_mul_f32_e32 v27, v114, v27
	v_mul_f32_e32 v28, v115, v28
	v_mul_f32_e32 v29, v115, v29
	v_mul_f32_e32 v30, v115, v30
	v_mul_f32_e32 v31, v115, v31
	v_mul_f32_e32 v32, v116, v32
	v_mul_f32_e32 v33, v116, v33
	v_mul_f32_e32 v34, v116, v34
	v_mul_f32_e32 v35, v116, v35
	v_mul_f32_e32 v36, v117, v36
	v_mul_f32_e32 v37, v117, v37
	v_mul_f32_e32 v38, v117, v38
	v_mul_f32_e32 v39, v117, v39
	v_mul_f32_e32 v40, v118, v40
	v_mul_f32_e32 v41, v118, v41
	v_mul_f32_e32 v42, v118, v42
	v_mul_f32_e32 v43, v118, v43
	v_mul_f32_e32 v44, v119, v44
	v_mul_f32_e32 v45, v119, v45
	v_mul_f32_e32 v46, v119, v46
	v_mul_f32_e32 v47, v119, v47
	v_cvt_pk_bf16_f32 v80, v16, v20
	v_cvt_pk_bf16_f32 v81, v24, v28
	v_cvt_pk_bf16_f32 v82, v32, v36
	v_cvt_pk_bf16_f32 v83, v40, v44
	v_cvt_pk_bf16_f32 v84, v17, v21
	v_cvt_pk_bf16_f32 v85, v25, v29
	v_cvt_pk_bf16_f32 v86, v33, v37
	v_cvt_pk_bf16_f32 v87, v41, v45
	v_cvt_pk_bf16_f32 v88, v18, v22
	v_cvt_pk_bf16_f32 v89, v26, v30
	v_cvt_pk_bf16_f32 v90, v34, v38
	v_cvt_pk_bf16_f32 v91, v42, v46
	v_cvt_pk_bf16_f32 v92, v19, v23
	v_cvt_pk_bf16_f32 v93, v27, v31
	v_cvt_pk_bf16_f32 v94, v35, v39
	v_cvt_pk_bf16_f32 v95, v43, v47
	v_lshlrev_b32_e32 v152, 16, v80
	v_and_b32_e32 v153, 0xffff0000, v80
	v_add_f32_e32 v144, v144, v152
	v_add_f32_e32 v144, v144, v153
	v_lshlrev_b32_e32 v152, 16, v81
	v_and_b32_e32 v153, 0xffff0000, v81
	v_add_f32_e32 v144, v144, v152
	v_add_f32_e32 v144, v144, v153
	v_lshlrev_b32_e32 v152, 16, v82
	v_and_b32_e32 v153, 0xffff0000, v82
	v_add_f32_e32 v144, v144, v152
	v_add_f32_e32 v144, v144, v153
	v_lshlrev_b32_e32 v152, 16, v83
	v_and_b32_e32 v153, 0xffff0000, v83
	v_add_f32_e32 v144, v144, v152
	v_add_f32_e32 v144, v144, v153
	v_lshlrev_b32_e32 v152, 16, v84
	v_and_b32_e32 v153, 0xffff0000, v84
	v_add_f32_e32 v145, v145, v152
	v_add_f32_e32 v145, v145, v153
	v_lshlrev_b32_e32 v152, 16, v85
	v_and_b32_e32 v153, 0xffff0000, v85
	v_add_f32_e32 v145, v145, v152
	v_add_f32_e32 v145, v145, v153
	v_lshlrev_b32_e32 v152, 16, v86
	v_and_b32_e32 v153, 0xffff0000, v86
	v_add_f32_e32 v145, v145, v152
	v_add_f32_e32 v145, v145, v153
	v_lshlrev_b32_e32 v152, 16, v87
	v_and_b32_e32 v153, 0xffff0000, v87
	v_add_f32_e32 v145, v145, v152
	v_add_f32_e32 v145, v145, v153
	v_lshlrev_b32_e32 v152, 16, v88
	v_and_b32_e32 v153, 0xffff0000, v88
	v_add_f32_e32 v146, v146, v152
	v_add_f32_e32 v146, v146, v153
	v_lshlrev_b32_e32 v152, 16, v89
	v_and_b32_e32 v153, 0xffff0000, v89
	v_add_f32_e32 v146, v146, v152
	v_add_f32_e32 v146, v146, v153
	v_lshlrev_b32_e32 v152, 16, v90
	v_and_b32_e32 v153, 0xffff0000, v90
	v_add_f32_e32 v146, v146, v152
	v_add_f32_e32 v146, v146, v153
	v_lshlrev_b32_e32 v152, 16, v91
	v_and_b32_e32 v153, 0xffff0000, v91
	v_add_f32_e32 v146, v146, v152
	v_add_f32_e32 v146, v146, v153
	v_lshlrev_b32_e32 v152, 16, v92
	v_and_b32_e32 v153, 0xffff0000, v92
	v_add_f32_e32 v147, v147, v152
	v_add_f32_e32 v147, v147, v153
	v_lshlrev_b32_e32 v152, 16, v93
	v_and_b32_e32 v153, 0xffff0000, v93
	v_add_f32_e32 v147, v147, v152
	v_add_f32_e32 v147, v147, v153
	v_lshlrev_b32_e32 v152, 16, v94
	v_and_b32_e32 v153, 0xffff0000, v94
	v_add_f32_e32 v147, v147, v152
	v_add_f32_e32 v147, v147, v153
	v_lshlrev_b32_e32 v152, 16, v95
	v_and_b32_e32 v153, 0xffff0000, v95
	v_add_f32_e32 v147, v147, v152
	v_add_f32_e32 v147, v147, v153
	ds_write_b128 v6, v[80:83] offset:0
	ds_write_b128 v6, v[84:87] offset:512
	ds_write_b128 v6, v[88:91] offset:1024
	ds_write_b128 v6, v[92:95] offset:1536
	s_waitcnt lgkmcnt(0)
	s_barrier
	ds_read_b128 v[96:99], v7
	ds_read_b128 v[100:103], v8
	ds_read_b128 v[104:107], v9
	ds_read_b128 v[108:111], v10
	s_cmp_gt_u32 s8, 2
	s_cbranch_scc0 .Lp0_g_skipst2
	s_waitcnt lgkmcnt(3)
	global_store_dwordx4 v5, v[96:99], s[34:35] offset:1024
	s_waitcnt lgkmcnt(2)
	global_store_dwordx4 v5, v[100:103], s[34:35] offset:1152
	s_bitcmp1_b32 s9, 1
	s_cbranch_scc1 .Lp0_g_skipst2
	s_waitcnt lgkmcnt(1)
	global_store_dwordx4 v5, v[104:107], s[34:35] offset:1280
	s_waitcnt lgkmcnt(0)
	global_store_dwordx4 v5, v[108:111], s[34:35] offset:1408
.Lp0_g_skipst2:
	s_waitcnt lgkmcnt(0)
	s_waitcnt vmcnt(0)
	v_fmac_f32_e32 v148, v136, v48
	v_fmac_f32_e32 v148, v137, v52
	v_fmac_f32_e32 v148, v138, v56
	v_fmac_f32_e32 v148, v139, v60
	v_fmac_f32_e32 v148, v140, v64
	v_fmac_f32_e32 v148, v141, v68
	v_fmac_f32_e32 v148, v142, v72
	v_fmac_f32_e32 v148, v143, v76
	v_fmac_f32_e32 v149, v136, v49
	v_fmac_f32_e32 v149, v137, v53
	v_fmac_f32_e32 v149, v138, v57
	v_fmac_f32_e32 v149, v139, v61
	v_fmac_f32_e32 v149, v140, v65
	v_fmac_f32_e32 v149, v141, v69
	v_fmac_f32_e32 v149, v142, v73
	v_fmac_f32_e32 v149, v143, v77
	v_fmac_f32_e32 v150, v136, v50
	v_fmac_f32_e32 v150, v137, v54
	v_fmac_f32_e32 v150, v138, v58
	v_fmac_f32_e32 v150, v139, v62
	v_fmac_f32_e32 v150, v140, v66
	v_fmac_f32_e32 v150, v141, v70
	v_fmac_f32_e32 v150, v142, v74
	v_fmac_f32_e32 v150, v143, v78
	v_fmac_f32_e32 v151, v136, v51
	v_fmac_f32_e32 v151, v137, v55
	v_fmac_f32_e32 v151, v138, v59
	v_fmac_f32_e32 v151, v139, v63
	v_fmac_f32_e32 v151, v140, v67
	v_fmac_f32_e32 v151, v141, v71
	v_fmac_f32_e32 v151, v142, v75
	v_fmac_f32_e32 v151, v143, v79
	v_mul_f32_e32 v48, v128, v48
	v_mul_f32_e32 v49, v128, v49
	v_mul_f32_e32 v50, v128, v50
	v_mul_f32_e32 v51, v128, v51
	v_mul_f32_e32 v52, v129, v52
	v_mul_f32_e32 v53, v129, v53
	v_mul_f32_e32 v54, v129, v54
	v_mul_f32_e32 v55, v129, v55
	v_mul_f32_e32 v56, v130, v56
	v_mul_f32_e32 v57, v130, v57
	v_mul_f32_e32 v58, v130, v58
	v_mul_f32_e32 v59, v130, v59
	v_mul_f32_e32 v60, v131, v60
	v_mul_f32_e32 v61, v131, v61
	v_mul_f32_e32 v62, v131, v62
	v_mul_f32_e32 v63, v131, v63
	v_mul_f32_e32 v64, v132, v64
	v_mul_f32_e32 v65, v132, v65
	v_mul_f32_e32 v66, v132, v66
	v_mul_f32_e32 v67, v132, v67
	v_mul_f32_e32 v68, v133, v68
	v_mul_f32_e32 v69, v133, v69
	v_mul_f32_e32 v70, v133, v70
	v_mul_f32_e32 v71, v133, v71
	v_mul_f32_e32 v72, v134, v72
	v_mul_f32_e32 v73, v134, v73
	v_mul_f32_e32 v74, v134, v74
	v_mul_f32_e32 v75, v134, v75
	v_mul_f32_e32 v76, v135, v76
	v_mul_f32_e32 v77, v135, v77
	v_mul_f32_e32 v78, v135, v78
	v_mul_f32_e32 v79, v135, v79
	v_cvt_pk_bf16_f32 v80, v48, v52
	v_cvt_pk_bf16_f32 v81, v56, v60
	v_cvt_pk_bf16_f32 v82, v64, v68
	v_cvt_pk_bf16_f32 v83, v72, v76
	v_cvt_pk_bf16_f32 v84, v49, v53
	v_cvt_pk_bf16_f32 v85, v57, v61
	v_cvt_pk_bf16_f32 v86, v65, v69
	v_cvt_pk_bf16_f32 v87, v73, v77
	v_cvt_pk_bf16_f32 v88, v50, v54
	v_cvt_pk_bf16_f32 v89, v58, v62
	v_cvt_pk_bf16_f32 v90, v66, v70
	v_cvt_pk_bf16_f32 v91, v74, v78
	v_cvt_pk_bf16_f32 v92, v51, v55
	v_cvt_pk_bf16_f32 v93, v59, v63
	v_cvt_pk_bf16_f32 v94, v67, v71
	v_cvt_pk_bf16_f32 v95, v75, v79
	v_lshlrev_b32_e32 v152, 16, v80
	v_and_b32_e32 v153, 0xffff0000, v80
	v_add_f32_e32 v144, v144, v152
	v_add_f32_e32 v144, v144, v153
	v_lshlrev_b32_e32 v152, 16, v81
	v_and_b32_e32 v153, 0xffff0000, v81
	v_add_f32_e32 v144, v144, v152
	v_add_f32_e32 v144, v144, v153
	v_lshlrev_b32_e32 v152, 16, v82
	v_and_b32_e32 v153, 0xffff0000, v82
	v_add_f32_e32 v144, v144, v152
	v_add_f32_e32 v144, v144, v153
	v_lshlrev_b32_e32 v152, 16, v83
	v_and_b32_e32 v153, 0xffff0000, v83
	v_add_f32_e32 v144, v144, v152
	v_add_f32_e32 v144, v144, v153
	v_lshlrev_b32_e32 v152, 16, v84
	v_and_b32_e32 v153, 0xffff0000, v84
	v_add_f32_e32 v145, v145, v152
	v_add_f32_e32 v145, v145, v153
	v_lshlrev_b32_e32 v152, 16, v85
	v_and_b32_e32 v153, 0xffff0000, v85
	v_add_f32_e32 v145, v145, v152
	v_add_f32_e32 v145, v145, v153
	v_lshlrev_b32_e32 v152, 16, v86
	v_and_b32_e32 v153, 0xffff0000, v86
	v_add_f32_e32 v145, v145, v152
	v_add_f32_e32 v145, v145, v153
	v_lshlrev_b32_e32 v152, 16, v87
	v_and_b32_e32 v153, 0xffff0000, v87
	v_add_f32_e32 v145, v145, v152
	v_add_f32_e32 v145, v145, v153
	v_lshlrev_b32_e32 v152, 16, v88
	v_and_b32_e32 v153, 0xffff0000, v88
	v_add_f32_e32 v146, v146, v152
	v_add_f32_e32 v146, v146, v153
	v_lshlrev_b32_e32 v152, 16, v89
	v_and_b32_e32 v153, 0xffff0000, v89
	v_add_f32_e32 v146, v146, v152
	v_add_f32_e32 v146, v146, v153
	v_lshlrev_b32_e32 v152, 16, v90
	v_and_b32_e32 v153, 0xffff0000, v90
	v_add_f32_e32 v146, v146, v152
	v_add_f32_e32 v146, v146, v153
	v_lshlrev_b32_e32 v152, 16, v91
	v_and_b32_e32 v153, 0xffff0000, v91
	v_add_f32_e32 v146, v146, v152
	v_add_f32_e32 v146, v146, v153
	v_lshlrev_b32_e32 v152, 16, v92
	v_and_b32_e32 v153, 0xffff0000, v92
	v_add_f32_e32 v147, v147, v152
	v_add_f32_e32 v147, v147, v153
	v_lshlrev_b32_e32 v152, 16, v93
	v_and_b32_e32 v153, 0xffff0000, v93
	v_add_f32_e32 v147, v147, v152
	v_add_f32_e32 v147, v147, v153
	v_lshlrev_b32_e32 v152, 16, v94
	v_and_b32_e32 v153, 0xffff0000, v94
	v_add_f32_e32 v147, v147, v152
	v_add_f32_e32 v147, v147, v153
	v_lshlrev_b32_e32 v152, 16, v95
	v_and_b32_e32 v153, 0xffff0000, v95
	v_add_f32_e32 v147, v147, v152
	v_add_f32_e32 v147, v147, v153
	ds_write_b128 v6, v[80:83] offset:32768
	ds_write_b128 v6, v[84:87] offset:33280
	ds_write_b128 v6, v[88:91] offset:33792
	ds_write_b128 v6, v[92:95] offset:34304
	s_waitcnt lgkmcnt(0)
	s_barrier
	ds_read_b128 v[96:99], v7 offset:32768
	ds_read_b128 v[100:103], v8 offset:32768
	ds_read_b128 v[104:107], v9 offset:32768
	ds_read_b128 v[108:111], v10 offset:32768
	s_cmp_gt_u32 s8, 3
	s_cbranch_scc0 .Lp0_g_skipst3
	s_waitcnt lgkmcnt(3)
	global_store_dwordx4 v5, v[96:99], s[34:35] offset:1536
	s_waitcnt lgkmcnt(2)
	global_store_dwordx4 v5, v[100:103], s[34:35] offset:1664
	s_bitcmp1_b32 s9, 1
	s_cbranch_scc1 .Lp0_g_skipst3
	s_waitcnt lgkmcnt(1)
	global_store_dwordx4 v5, v[104:107], s[34:35] offset:1792
	s_waitcnt lgkmcnt(0)
	global_store_dwordx4 v5, v[108:111], s[34:35] offset:1920
.Lp0_g_skipst3:
	s_waitcnt lgkmcnt(0)
	v_lshlrev_b32_e32 v152, 8, v3
	v_lshl_add_u32 v152, v2, 4, v152
	v_add_u32_e32 v152, 0x10000, v152
	ds_write_b128 v152, v[144:147]
	ds_write_b128 v152, v[148:151] offset:8192
	s_waitcnt lgkmcnt(0)
	s_barrier
	v_cmp_gt_u32_e32 vcc, 64, v162
	s_and_saveexec_b64 s[4:5], vcc
	s_cbranch_execz .Lp0_gate_done
	v_lshlrev_b32_e32 v152, 2, v162
	v_add_u32_e32 v153, 0x10000, v152
	ds_read_b32 v16, v153
	ds_read_b32 v17, v153 offset:256
	ds_read_b32 v18, v153 offset:512
	ds_read_b32 v19, v153 offset:768
	ds_read_b32 v20, v153 offset:1024
	ds_read_b32 v21, v153 offset:1280
	ds_read_b32 v22, v153 offset:1536
	ds_read_b32 v23, v153 offset:1792
	ds_read_b32 v24, v153 offset:2048
	ds_read_b32 v25, v153 offset:2304
	ds_read_b32 v26, v153 offset:2560
	ds_read_b32 v27, v153 offset:2816
	ds_read_b32 v28, v153 offset:3072
	ds_read_b32 v29, v153 offset:3328
	ds_read_b32 v30, v153 offset:3584
	ds_read_b32 v31, v153 offset:3840
	ds_read_b32 v32, v153 offset:4096
	ds_read_b32 v33, v153 offset:4352
	ds_read_b32 v34, v153 offset:4608
	ds_read_b32 v35, v153 offset:4864
	ds_read_b32 v36, v153 offset:5120
	ds_read_b32 v37, v153 offset:5376
	ds_read_b32 v38, v153 offset:5632
	ds_read_b32 v39, v153 offset:5888
	ds_read_b32 v40, v153 offset:6144
	ds_read_b32 v41, v153 offset:6400
	ds_read_b32 v42, v153 offset:6656
	ds_read_b32 v43, v153 offset:6912
	ds_read_b32 v44, v153 offset:7168
	ds_read_b32 v45, v153 offset:7424
	ds_read_b32 v46, v153 offset:7680
	ds_read_b32 v47, v153 offset:7936
	s_waitcnt lgkmcnt(0)
	v_mov_b32_e32 v154, 0
	v_add_f32_e32 v154, v154, v16
	v_add_f32_e32 v154, v154, v17
	v_add_f32_e32 v154, v154, v18
	v_add_f32_e32 v154, v154, v19
	v_add_f32_e32 v154, v154, v20
	v_add_f32_e32 v154, v154, v21
	v_add_f32_e32 v154, v154, v22
	v_add_f32_e32 v154, v154, v23
	v_add_f32_e32 v154, v154, v24
	v_add_f32_e32 v154, v154, v25
	v_add_f32_e32 v154, v154, v26
	v_add_f32_e32 v154, v154, v27
	v_add_f32_e32 v154, v154, v28
	v_add_f32_e32 v154, v154, v29
	v_add_f32_e32 v154, v154, v30
	v_add_f32_e32 v154, v154, v31
	v_add_f32_e32 v154, v154, v32
	v_add_f32_e32 v154, v154, v33
	v_add_f32_e32 v154, v154, v34
	v_add_f32_e32 v154, v154, v35
	v_add_f32_e32 v154, v154, v36
	v_add_f32_e32 v154, v154, v37
	v_add_f32_e32 v154, v154, v38
	v_add_f32_e32 v154, v154, v39
	v_add_f32_e32 v154, v154, v40
	v_add_f32_e32 v154, v154, v41
	v_add_f32_e32 v154, v154, v42
	v_add_f32_e32 v154, v154, v43
	v_add_f32_e32 v154, v154, v44
	v_add_f32_e32 v154, v154, v45
	v_add_f32_e32 v154, v154, v46
	v_add_f32_e32 v154, v154, v47
	ds_read_b32 v16, v153 offset:8192
	ds_read_b32 v17, v153 offset:8448
	ds_read_b32 v18, v153 offset:8704
	ds_read_b32 v19, v153 offset:8960
	ds_read_b32 v20, v153 offset:9216
	ds_read_b32 v21, v153 offset:9472
	ds_read_b32 v22, v153 offset:9728
	ds_read_b32 v23, v153 offset:9984
	ds_read_b32 v24, v153 offset:10240
	ds_read_b32 v25, v153 offset:10496
	ds_read_b32 v26, v153 offset:10752
	ds_read_b32 v27, v153 offset:11008
	ds_read_b32 v28, v153 offset:11264
	ds_read_b32 v29, v153 offset:11520
	ds_read_b32 v30, v153 offset:11776
	ds_read_b32 v31, v153 offset:12032
	ds_read_b32 v32, v153 offset:12288
	ds_read_b32 v33, v153 offset:12544
	ds_read_b32 v34, v153 offset:12800
	ds_read_b32 v35, v153 offset:13056
	ds_read_b32 v36, v153 offset:13312
	ds_read_b32 v37, v153 offset:13568
	ds_read_b32 v38, v153 offset:13824
	ds_read_b32 v39, v153 offset:14080
	ds_read_b32 v40, v153 offset:14336
	ds_read_b32 v41, v153 offset:14592
	ds_read_b32 v42, v153 offset:14848
	ds_read_b32 v43, v153 offset:15104
	ds_read_b32 v44, v153 offset:15360
	ds_read_b32 v45, v153 offset:15616
	ds_read_b32 v46, v153 offset:15872
	ds_read_b32 v47, v153 offset:16128
	s_waitcnt lgkmcnt(0)
	v_mov_b32_e32 v155, 0
	v_add_f32_e32 v155, v155, v16
	v_add_f32_e32 v155, v155, v17
	v_add_f32_e32 v155, v155, v18
	v_add_f32_e32 v155, v155, v19
	v_add_f32_e32 v155, v155, v20
	v_add_f32_e32 v155, v155, v21
	v_add_f32_e32 v155, v155, v22
	v_add_f32_e32 v155, v155, v23
	v_add_f32_e32 v155, v155, v24
	v_add_f32_e32 v155, v155, v25
	v_add_f32_e32 v155, v155, v26
	v_add_f32_e32 v155, v155, v27
	v_add_f32_e32 v155, v155, v28
	v_add_f32_e32 v155, v155, v29
	v_add_f32_e32 v155, v155, v30
	v_add_f32_e32 v155, v155, v31
	v_add_f32_e32 v155, v155, v32
	v_add_f32_e32 v155, v155, v33
	v_add_f32_e32 v155, v155, v34
	v_add_f32_e32 v155, v155, v35
	v_add_f32_e32 v155, v155, v36
	v_add_f32_e32 v155, v155, v37
	v_add_f32_e32 v155, v155, v38
	v_add_f32_e32 v155, v155, v39
	v_add_f32_e32 v155, v155, v40
	v_add_f32_e32 v155, v155, v41
	v_add_f32_e32 v155, v155, v42
	v_add_f32_e32 v155, v155, v43
	v_add_f32_e32 v155, v155, v44
	v_add_f32_e32 v155, v155, v45
	v_add_f32_e32 v155, v155, v46
	v_add_f32_e32 v155, v155, v47
	global_store_dword v152, v154, s[42:43]
	global_store_dword v152, v155, s[44:45]

.Lp0_xconv:
	s_cmpk_lt_u32 s92, 0x88
	s_cbranch_scc0 .Lp0_x1
	s_mul_i32 s0, s92, 12
	s_mov_b32 s1, 12
	s_branch .Lp0_xgo
.Lp0_x1:
	s_cmpk_lt_u32 s92, 0xb8
	s_cbranch_scc0 .Lp0_x2
	s_sub_u32 s0, s92, 0x88
	s_lshl_b32 s0, s0, 4
	s_add_u32 s0, s0, 1632
	s_mov_b32 s1, 16
	s_branch .Lp0_xgo
.Lp0_x2:
	s_cmpk_lt_u32 s92, 0xc8
	s_cbranch_scc0 .Lp0_x3
	s_sub_u32 s0, s92, 0xb8
	s_mul_i32 s0, s0, 20
	s_add_u32 s0, s0, 2400
	s_mov_b32 s1, 20
	s_branch .Lp0_xgo
.Lp0_x3:
	s_sub_u32 s0, s92, 0xc8
	s_mul_i32 s0, s0, 28
	s_add_u32 s0, s0, 2720
	s_mov_b32 s1, 28
.Lp0_xgo:
	s_add_u32 s2, s0, s1
	s_min_u32 s2, s2, 4160
	s_cmp_lt_u32 s0, s2
	s_cbranch_scc0 .Lp0_stzero
	s_sub_u32 s50, s2, s0
	s_lshr_b32 s50, s50, 1
	v_readlane_b32 s56, v251, 24
	v_readlane_b32 s57, v251, 25
	v_readlane_b32 s58, v251, 26
	v_readlane_b32 s59, v251, 27
	s_mov_b32 s3, s0
	s_lshl_b32 s1, s0, 13
	s_add_u32 s1, s1, 0x1700000
	s_add_u32 s48, s86, s1
	s_addc_u32 s49, s87, 0
	v_lshlrev_b32_e32 v4, 5, v162
	v_lshlrev_b32_e32 v5, 4, v162
	v_add_u32_e32 v12, 0x2000, v5
	s_cmpk_lt_u32 s3, 0x1000
	s_cselect_b32 s6, s56, s58
	s_cselect_b32 s7, s57, s59
	s_cselect_b32 s2, 0, 0x1000
	s_sub_u32 s2, s3, s2
	s_lshr_b32 s1, s2, 18
	s_lshl_b32 s2, s2, 14
	s_add_u32 s16, s6, s2
	s_addc_u32 s17, s7, s1
	global_load_dwordx4 v[16:19], v4, s[16:17] nt
	global_load_dwordx4 v[20:23], v4, s[16:17] offset:16 nt
	s_add_u32 s16, s16, 0x4000
	s_addc_u32 s17, s17, 0
	global_load_dwordx4 v[24:27], v4, s[16:17] nt
	global_load_dwordx4 v[28:31], v4, s[16:17] offset:16 nt
	s_add_u32 s3, s3, 2
	s_cmpk_lt_u32 s3, 0x1000
	s_cselect_b32 s6, s56, s58
	s_cselect_b32 s7, s57, s59
	s_cselect_b32 s2, 0, 0x1000
	s_sub_u32 s2, s3, s2
	s_lshr_b32 s1, s2, 18
	s_lshl_b32 s2, s2, 14
	s_add_u32 s18, s6, s2
	s_addc_u32 s19, s7, s1
	global_load_dwordx4 v[32:35], v4, s[18:19] nt
	global_load_dwordx4 v[36:39], v4, s[18:19] offset:16 nt
	s_add_u32 s18, s18, 0x4000
	s_addc_u32 s19, s19, 0
	global_load_dwordx4 v[40:43], v4, s[18:19] nt
	global_load_dwordx4 v[44:47], v4, s[18:19] offset:16 nt
	s_add_u32 s3, s3, 2
	s_sub_u32 s50, s50, 2
.Lp0_xloop:
	s_cmp_eq_u32 s50, 0
	s_cbranch_scc1 .Lp0_xtail0
	s_cmpk_lt_u32 s3, 0x1000
	s_cselect_b32 s6, s56, s58
	s_cselect_b32 s7, s57, s59
	s_cselect_b32 s2, 0, 0x1000
	s_sub_u32 s2, s3, s2
	s_lshr_b32 s1, s2, 18
	s_lshl_b32 s2, s2, 14
	s_add_u32 s20, s6, s2
	s_addc_u32 s21, s7, s1
	global_load_dwordx4 v[48:51], v4, s[20:21] nt
	global_load_dwordx4 v[52:55], v4, s[20:21] offset:16 nt
	s_add_u32 s20, s20, 0x4000
	s_addc_u32 s21, s21, 0
	global_load_dwordx4 v[56:59], v4, s[20:21] nt
	global_load_dwordx4 v[60:63], v4, s[20:21] offset:16 nt
	s_add_u32 s3, s3, 2
	s_sub_u32 s50, s50, 1
	s_waitcnt vmcnt(8)
	v_cvt_pk_bf16_f32 v80, v16, v17
	v_cvt_pk_bf16_f32 v81, v18, v19
	v_cvt_pk_bf16_f32 v82, v20, v21
	v_cvt_pk_bf16_f32 v83, v22, v23
	v_cvt_pk_bf16_f32 v84, v24, v25
	v_cvt_pk_bf16_f32 v85, v26, v27
	v_cvt_pk_bf16_f32 v86, v28, v29
	v_cvt_pk_bf16_f32 v87, v30, v31
	global_store_dwordx4 v5, v[80:83], s[48:49]
	global_store_dwordx4 v12, v[84:87], s[48:49]
	s_add_u32 s48, s48, 0x4000
	s_addc_u32 s49, s49, 0
	s_cmp_eq_u32 s50, 0
	s_cbranch_scc1 .Lp0_xtail1
	s_cmpk_lt_u32 s3, 0x1000
	s_cselect_b32 s6, s56, s58
	s_cselect_b32 s7, s57, s59
	s_cselect_b32 s2, 0, 0x1000
	s_sub_u32 s2, s3, s2
	s_lshr_b32 s1, s2, 18
	s_lshl_b32 s2, s2, 14
	s_add_u32 s16, s6, s2
	s_addc_u32 s17, s7, s1
	global_load_dwordx4 v[16:19], v4, s[16:17] nt
	global_load_dwordx4 v[20:23], v4, s[16:17] offset:16 nt
	s_add_u32 s16, s16, 0x4000
	s_addc_u32 s17, s17, 0
	global_load_dwordx4 v[24:27], v4, s[16:17] nt
	global_load_dwordx4 v[28:31], v4, s[16:17] offset:16 nt
	s_add_u32 s3, s3, 2
	s_sub_u32 s50, s50, 1
	s_waitcnt vmcnt(8)
	v_cvt_pk_bf16_f32 v80, v32, v33
	v_cvt_pk_bf16_f32 v81, v34, v35
	v_cvt_pk_bf16_f32 v82, v36, v37
	v_cvt_pk_bf16_f32 v83, v38, v39
	v_cvt_pk_bf16_f32 v84, v40, v41
	v_cvt_pk_bf16_f32 v85, v42, v43
	v_cvt_pk_bf16_f32 v86, v44, v45
	v_cvt_pk_bf16_f32 v87, v46, v47
	global_store_dwordx4 v5, v[80:83], s[48:49]
	global_store_dwordx4 v12, v[84:87], s[48:49]
	s_add_u32 s48, s48, 0x4000
	s_addc_u32 s49, s49, 0
	s_cmp_eq_u32 s50, 0
	s_cbranch_scc1 .Lp0_xtail2
	s_cmpk_lt_u32 s3, 0x1000
	s_cselect_b32 s6, s56, s58
	s_cselect_b32 s7, s57, s59
	s_cselect_b32 s2, 0, 0x1000
	s_sub_u32 s2, s3, s2
	s_lshr_b32 s1, s2, 18
	s_lshl_b32 s2, s2, 14
	s_add_u32 s18, s6, s2
	s_addc_u32 s19, s7, s1
	global_load_dwordx4 v[32:35], v4, s[18:19] nt
	global_load_dwordx4 v[36:39], v4, s[18:19] offset:16 nt
	s_add_u32 s18, s18, 0x4000
	s_addc_u32 s19, s19, 0
	global_load_dwordx4 v[40:43], v4, s[18:19] nt
	global_load_dwordx4 v[44:47], v4, s[18:19] offset:16 nt
	s_add_u32 s3, s3, 2
	s_sub_u32 s50, s50, 1
	s_waitcnt vmcnt(8)
	v_cvt_pk_bf16_f32 v80, v48, v49
	v_cvt_pk_bf16_f32 v81, v50, v51
	v_cvt_pk_bf16_f32 v82, v52, v53
	v_cvt_pk_bf16_f32 v83, v54, v55
	v_cvt_pk_bf16_f32 v84, v56, v57
	v_cvt_pk_bf16_f32 v85, v58, v59
	v_cvt_pk_bf16_f32 v86, v60, v61
	v_cvt_pk_bf16_f32 v87, v62, v63
	global_store_dwordx4 v5, v[80:83], s[48:49]
	global_store_dwordx4 v12, v[84:87], s[48:49]
	s_add_u32 s48, s48, 0x4000
	s_addc_u32 s49, s49, 0
	s_branch .Lp0_xloop
.Lp0_xtail0:
	s_waitcnt vmcnt(4)
	v_cvt_pk_bf16_f32 v80, v16, v17
	v_cvt_pk_bf16_f32 v81, v18, v19
	v_cvt_pk_bf16_f32 v82, v20, v21
	v_cvt_pk_bf16_f32 v83, v22, v23
	v_cvt_pk_bf16_f32 v84, v24, v25
	v_cvt_pk_bf16_f32 v85, v26, v27
	v_cvt_pk_bf16_f32 v86, v28, v29
	v_cvt_pk_bf16_f32 v87, v30, v31
	global_store_dwordx4 v5, v[80:83], s[48:49]
	global_store_dwordx4 v12, v[84:87], s[48:49]
	s_add_u32 s48, s48, 0x4000
	s_addc_u32 s49, s49, 0
	s_waitcnt vmcnt(2)
	v_cvt_pk_bf16_f32 v80, v32, v33
	v_cvt_pk_bf16_f32 v81, v34, v35
	v_cvt_pk_bf16_f32 v82, v36, v37
	v_cvt_pk_bf16_f32 v83, v38, v39
	v_cvt_pk_bf16_f32 v84, v40, v41
	v_cvt_pk_bf16_f32 v85, v42, v43
	v_cvt_pk_bf16_f32 v86, v44, v45
	v_cvt_pk_bf16_f32 v87, v46, v47
	global_store_dwordx4 v5, v[80:83], s[48:49]
	global_store_dwordx4 v12, v[84:87], s[48:49]
	s_add_u32 s48, s48, 0x4000
	s_addc_u32 s49, s49, 0
	s_branch .Lp0_stzero
.Lp0_xtail1:
	s_waitcnt vmcnt(4)
	v_cvt_pk_bf16_f32 v80, v32, v33
	v_cvt_pk_bf16_f32 v81, v34, v35
	v_cvt_pk_bf16_f32 v82, v36, v37
	v_cvt_pk_bf16_f32 v83, v38, v39
	v_cvt_pk_bf16_f32 v84, v40, v41
	v_cvt_pk_bf16_f32 v85, v42, v43
	v_cvt_pk_bf16_f32 v86, v44, v45
	v_cvt_pk_bf16_f32 v87, v46, v47
	global_store_dwordx4 v5, v[80:83], s[48:49]
	global_store_dwordx4 v12, v[84:87], s[48:49]
	s_add_u32 s48, s48, 0x4000
	s_addc_u32 s49, s49, 0
	s_waitcnt vmcnt(2)
	v_cvt_pk_bf16_f32 v80, v48, v49
	v_cvt_pk_bf16_f32 v81, v50, v51
	v_cvt_pk_bf16_f32 v82, v52, v53
	v_cvt_pk_bf16_f32 v83, v54, v55
	v_cvt_pk_bf16_f32 v84, v56, v57
	v_cvt_pk_bf16_f32 v85, v58, v59
	v_cvt_pk_bf16_f32 v86, v60, v61
	v_cvt_pk_bf16_f32 v87, v62, v63
	global_store_dwordx4 v5, v[80:83], s[48:49]
	global_store_dwordx4 v12, v[84:87], s[48:49]
	s_add_u32 s48, s48, 0x4000
	s_addc_u32 s49, s49, 0
	s_branch .Lp0_stzero
.Lp0_xtail2:
	s_waitcnt vmcnt(4)
	v_cvt_pk_bf16_f32 v80, v48, v49
	v_cvt_pk_bf16_f32 v81, v50, v51
	v_cvt_pk_bf16_f32 v82, v52, v53
	v_cvt_pk_bf16_f32 v83, v54, v55
	v_cvt_pk_bf16_f32 v84, v56, v57
	v_cvt_pk_bf16_f32 v85, v58, v59
	v_cvt_pk_bf16_f32 v86, v60, v61
	v_cvt_pk_bf16_f32 v87, v62, v63
	global_store_dwordx4 v5, v[80:83], s[48:49]
	global_store_dwordx4 v12, v[84:87], s[48:49]
	s_add_u32 s48, s48, 0x4000
	s_addc_u32 s49, s49, 0
	s_waitcnt vmcnt(2)
	v_cvt_pk_bf16_f32 v80, v16, v17
	v_cvt_pk_bf16_f32 v81, v18, v19
	v_cvt_pk_bf16_f32 v82, v20, v21
	v_cvt_pk_bf16_f32 v83, v22, v23
	v_cvt_pk_bf16_f32 v84, v24, v25
	v_cvt_pk_bf16_f32 v85, v26, v27
	v_cvt_pk_bf16_f32 v86, v28, v29
	v_cvt_pk_bf16_f32 v87, v30, v31
	global_store_dwordx4 v5, v[80:83], s[48:49]
	global_store_dwordx4 v12, v[84:87], s[48:49]
	s_add_u32 s48, s48, 0x4000
	s_addc_u32 s49, s49, 0
	s_branch .Lp0_stzero
.Lp0_stzero:
	v_lshl_add_u32 v152, s92, 9, v162
	v_cmp_gt_u32_e32 vcc, 0x4100, v152
	s_and_saveexec_b64 s[4:5], vcc
	s_cbranch_execz .Lp0_end
	v_lshlrev_b32_e32 v152, 4, v152
	v_mov_b32_e32 v16, 0
	v_mov_b32_e32 v17, 0
	v_mov_b32_e32 v18, 0
	v_mov_b32_e32 v19, 0
	global_store_dwordx4 v152, v[16:19], s[82:83]
.Lp0_end:
	s_or_b64 exec, exec, s[4:5]
.LBB0_144:
	s_add_u32 s58, s86, 0x1700000
	s_addc_u32 s59, s87, 0
	s_add_u32 s94, s86, 0x7060000
	s_addc_u32 s95, s87, 0
	s_add_u32 s44, s86, 0xa120000
	s_addc_u32 s45, s87, 0
	s_cmp_lt_i32 s88, 2
	s_cselect_b64 s[16:17], -1, 0
	s_cmp_gt_i32 s89, 1
	s_cselect_b64 s[0:1], -1, 0
	s_and_b64 s[0:1], s[16:17], s[0:1]
	s_andn2_b64 vcc, exec, s[0:1]
	v_writelane_b32 v251, s58, 40
	s_nop 1
	v_writelane_b32 v251, s59, 41
	s_cbranch_vccnz .LBB0_599
	s_andn2_b64 vcc, exec, s[10:11]
	s_cbranch_vccnz .LBB0_213
	s_cmp_gt_i32 s88, -1
	s_mov_b64 s[0:1], -1
	s_cbranch_scc0 .LBB0_200
	s_waitcnt vmcnt(0)
	s_barrier
	s_mov_b64 s[0:1], exec
	v_readlane_b32 s2, v251, 3
	v_readlane_b32 s3, v251, 4
	s_and_b64 s[2:3], s[0:1], s[2:3]
	s_mov_b64 exec, s[2:3]
	s_cbranch_execz .LBB0_199
	v_mov_b32_e32 v1, 0x20000
	s_waitcnt vmcnt(0) expcnt(0) lgkmcnt(0)
	ds_read_b32 v3, v1
	v_mov_b32_e32 v1, 0x20004
	ds_read_b32 v1, v1
	s_waitcnt lgkmcnt(1)
	v_cmp_ne_u32_e32 vcc, 0, v3
	s_cbranch_vccnz .LBB0_163
	v_readlane_b32 s2, v251, 0
	s_mul_i32 s33, s91, s2
	s_add_u32 s2, s86, 0x16ec200
	s_addc_u32 s3, s87, 0
	s_add_u32 s4, s86, 0x16ec400
	s_addc_u32 s5, s87, 0
	s_add_u32 s6, s86, 0x16ec500
	s_addc_u32 s7, s87, 0
	s_add_u32 s8, s86, 0x16ec600
	s_addc_u32 s9, s87, 0
	s_add_u32 s10, s86, 0x16ec700
	s_addc_u32 s11, s87, 0
	s_add_u32 s12, s86, 0x16ec800
	s_addc_u32 s13, s87, 0
	s_add_u32 s14, s86, 0x16ec900
	s_addc_u32 s15, s87, 0
	s_add_u32 s18, s86, 0x16eca00
	s_addc_u32 s19, s87, 0
	s_add_u32 s20, s86, 0x16ecb00
	s_addc_u32 s21, s87, 0
	s_add_u32 s22, s86, 0x16ecc00
	s_addc_u32 s23, s87, 0
	s_add_u32 s24, s86, 0x16ecd00
	s_addc_u32 s25, s87, 0
	s_add_u32 s26, s86, 0x16ece00
	s_addc_u32 s27, s87, 0
	s_add_u32 s28, s86, 0x16ecf00
	s_addc_u32 s29, s87, 0
	s_add_u32 s30, s86, 0x16ed000
	s_addc_u32 s31, s87, 0
	s_add_u32 s34, s86, 0x16ed100
	s_addc_u32 s35, s87, 0
	s_add_u32 s38, s86, 0x16ed200
	s_addc_u32 s39, s87, 0
	s_add_u32 s40, s86, 0x16ed300
	s_mul_i32 s33, s33, s90
	s_addc_u32 s41, s87, 0
	s_mov_b32 s36, 1
	v_mov_b32_e32 v17, 0
	s_branch .LBB0_151
